# v38 + same unit-start wait relaxation in the residual (down / out-proj) GEMM: K-loop restart no longer waits for the epilogue's float-atomic acks
# baseline (speedup 1.0000x reference)
; #define PG8_STAGE(bufoff, gbase, voff) do { _Pragma("unroll") for (int _i = 0; _i < 2; ++_i) \
;         __builtin_amdgcn_global_load_lds((const unsigned*)((const char*)(gbase) + (voff)[_i]), (PG8_LAS unsigned*)(lds + (bufoff) + ldsw + _i * 8192), 16, 0, 0); } while (0)
; #define PG8_LDA(dst, b, h) do { _Pragma("unroll") for (int m = 0; m < 4; ++m) _Pragma("unroll") for (int k = 0; k < 2; ++k) dst[m][k] = *(const PG8_LAS bf16x8*)(lds + PG8_SA(b, h) + aoff + m * 2048 + k * 1024); } while (0)
; #define PG8_LDB(dst, b, h) do { _Pragma("unroll") for (int n = 0; n < 2; ++n) _Pragma("unroll") for (int k = 0; k < 2; ++k) dst[n][k] = *(const PG8_LAS bf16x8*)(lds + PG8_SB(b, h) + boff + n * 2048 + k * 1024); } while (0)
; #define PG8_MMA(ai, bj, At, Bt) do { __builtin_amdgcn_s_setprio(1); _Pragma("unroll") for (int m = 0; m < 4; ++m) _Pragma("unroll") for (int n = 0; n < 2; ++n) _Pragma("unroll") for (int k = 0; k < 2; ++k) \
;         acc[ai][bj][m][n] = __builtin_amdgcn_mfma_f32_16x16x32_bf16(Bt[n][k], At[m][k], acc[ai][bj][m][n], 0, 0, 0); __builtin_amdgcn_s_setprio(0); } while (0)
; #define PG8_WAIT_V(n) asm volatile("s_waitcnt vmcnt(" #n ")" ::: "memory")
; #define PG8_WAIT_L(n) asm volatile("s_waitcnt lgkmcnt(" #n ")" ::: "memory")
; #define PG8_BAR __builtin_amdgcn_s_barrier()
; #define PG8_SCHED __builtin_amdgcn_sched_barrier(0)
; template <class Epi, class Sched, bool ALIGN_EPI = false, bool SP2 = false>
; __device__ __forceinline__ void gemm_phase(PG8_LAS unsigned char* lds, const int tid, const Gemm g, const Sched& S, const Epi& E) {
;     ...
;             const bool last = (t == nt - 2);
;             const char* a1 = cA + (size_t)(t + 1) * kstep;
;             const char* a2 = last ? nA : cA + (size_t)(t + 2) * kstep; const char* b2 = last ? nB : cB + (size_t)(t + 2) * kstep;
;             const char* a3 = a2 + kstep; const char* b3 = b2 + kstep;
;             if (last && has_next) S.a_ready(nxt);
;             if constexpr (SP2) {
;             PG8_LDB(B0, 0, 0); PG8_LDB(B1, 0, 1); PG8_SCHED; PG8_LDA(At, 0, 0); PG8_STAGE(PG8_SA(1, 1), a1 + hstep, voffA);
;             PG8_WAIT_V(8); PG8_WAIT_L(0); PG8_BAR; PG8_MMA(0, 0, At, B0); PG8_MMA(0, 1, At, B1); PG8_BAR; PG8_SCHED;
.LBB0_310:
	s_add_u32 s38, s26, 0x80
	s_addc_u32 s39, s27, 0
	s_add_u32 s26, s24, 0x100
	s_addc_u32 s27, s25, 0
	s_mov_b32 s14, 0
	s_waitcnt lgkmcnt(0)
	v_xor_b32_e32 v246, 64, v232
	v_add_u32_e32 v247, 0x10000, v185
	v_xor_b32_e32 v248, 64, v185
	v_add_u32_e32 v248, 0x10000, v248
	s_add_i32 s51, s14, 2
	s_add_u32 s10, s38, 0x80
	s_addc_u32 s24, s39, 0
	s_cmp_eq_u32 s47, s14
	s_cselect_b32 s25, s29, s24
	s_cselect_b32 s24, s28, s10
	s_cselect_b32 s53, s43, s27
	s_cselect_b32 s52, s42, s26
	s_add_u32 s92, s38, s12
	s_addc_u32 s93, s39, 0
	ds_read_b128 v[72:75], v247
	ds_read_b128 v[76:79], v248
	ds_read_b128 v[136:139], v247 offset:2048
	ds_read_b128 v[140:143], v248 offset:2048
	ds_read_b128 v[144:147], v247 offset:16384
	ds_read_b128 v[148:151], v248 offset:16384
	ds_read_b128 v[152:155], v247 offset:18432
	ds_read_b128 v[156:159], v248 offset:18432
	s_add_i32 m0, s20, 0xc000
	ds_read_b128 v[160:163], v232
	ds_read_b128 v[164:167], v246
	ds_read_b128 v[196:199], v232 offset:2048
	ds_read_b128 v[200:203], v246 offset:2048
	ds_read_b128 v[204:207], v232 offset:4096
	ds_read_b128 v[208:211], v246 offset:4096
	ds_read_b128 v[212:215], v232 offset:6144
	ds_read_b128 v[216:219], v246 offset:6144
	global_load_lds_dwordx4 v190, s[92:93]
	s_add_i32 m0, s20, 0xe000
	s_nop 0
	global_load_lds_dwordx4 v188, s[92:93]
	s_cmp_eq_u32 s48, 1
	s_cbranch_scc1 .Lstrict_g2_0
	s_waitcnt vmcnt(12)
	s_branch .Ljoinw_g2_0

; #define PG8_STAGE(bufoff, gbase, voff) do { _Pragma("unroll") for (int _i = 0; _i < 2; ++_i) \
;         __builtin_amdgcn_global_load_lds((const unsigned*)((const char*)(gbase) + (voff)[_i]), (PG8_LAS unsigned*)(lds + (bufoff) + ldsw + _i * 8192), 16, 0, 0); } while (0)
; #define PG8_LDA(dst, b, h) do { _Pragma("unroll") for (int m = 0; m < 4; ++m) _Pragma("unroll") for (int k = 0; k < 2; ++k) dst[m][k] = *(const PG8_LAS bf16x8*)(lds + PG8_SA(b, h) + aoff + m * 2048 + k * 1024); } while (0)
; #define PG8_MMA(ai, bj, At, Bt) do { __builtin_amdgcn_s_setprio(1); _Pragma("unroll") for (int m = 0; m < 4; ++m) _Pragma("unroll") for (int n = 0; n < 2; ++n) _Pragma("unroll") for (int k = 0; k < 2; ++k) \
;         acc[ai][bj][m][n] = __builtin_amdgcn_mfma_f32_16x16x32_bf16(Bt[n][k], At[m][k], acc[ai][bj][m][n], 0, 0, 0); __builtin_amdgcn_s_setprio(0); } while (0)
; #define PG8_WAIT_V(n) asm volatile("s_waitcnt vmcnt(" #n ")" ::: "memory")
; #define PG8_WAIT_L(n) asm volatile("s_waitcnt lgkmcnt(" #n ")" ::: "memory")
; #define PG8_BAR __builtin_amdgcn_s_barrier()
; #define PG8_SCHED __builtin_amdgcn_sched_barrier(0)
; template <class Epi, class Sched, bool ALIGN_EPI = false, bool SP2 = false>
; __device__ __forceinline__ void gemm_phase(PG8_LAS unsigned char* lds, const int tid, const Gemm g, const Sched& S, const Epi& E) {
;     ...
;             PG8_WAIT_V(8); PG8_WAIT_L(0); PG8_BAR; PG8_MMA(0, 0, At, B0); PG8_MMA(0, 1, At, B1); PG8_BAR; PG8_SCHED;
;             PG8_LDA(At, 0, 1); PG8_STAGE(PG8_SB(0, 0), b2, voffB); PG8_STAGE(PG8_SB(0, 1), b2 + hstep, voffB); PG8_STAGE(PG8_SA(0, 0), a2, voffA);
;             PG8_WAIT_V(8); PG8_WAIT_L(0); PG8_BAR; PG8_MMA(1, 0, At, B0); PG8_MMA(1, 1, At, B1); PG8_BAR; PG8_SCHED;
.Ljoinw_g2_0:
	s_waitcnt lgkmcnt(0)
	s_barrier
	s_setprio 1
	s_waitcnt lgkmcnt(0)
	v_mfma_f32_16x16x32_bf16 v[132:135], v[72:75], v[160:163], 0
	v_mfma_f32_16x16x32_bf16 v[128:131], v[136:139], v[160:163], 0
	v_mfma_f32_16x16x32_bf16 v[116:119], v[72:75], v[196:199], 0
	v_mfma_f32_16x16x32_bf16 v[112:115], v[136:139], v[196:199], 0
	v_mfma_f32_16x16x32_bf16 v[100:103], v[72:75], v[204:207], 0
	v_mfma_f32_16x16x32_bf16 v[96:99], v[136:139], v[204:207], 0
	v_mfma_f32_16x16x32_bf16 v[84:87], v[72:75], v[212:215], 0
	v_mfma_f32_16x16x32_bf16 v[80:83], v[136:139], v[212:215], 0
	v_mfma_f32_16x16x32_bf16 v[132:135], v[76:79], v[164:167], v[132:135]
	v_mfma_f32_16x16x32_bf16 v[128:131], v[140:143], v[164:167], v[128:131]
	v_mfma_f32_16x16x32_bf16 v[116:119], v[76:79], v[200:203], v[116:119]
	v_mfma_f32_16x16x32_bf16 v[112:115], v[140:143], v[200:203], v[112:115]
	v_mfma_f32_16x16x32_bf16 v[100:103], v[76:79], v[208:211], v[100:103]
	v_mfma_f32_16x16x32_bf16 v[96:99], v[140:143], v[208:211], v[96:99]
	v_mfma_f32_16x16x32_bf16 v[84:87], v[76:79], v[216:219], v[84:87]
	v_mfma_f32_16x16x32_bf16 v[80:83], v[140:143], v[216:219], v[80:83]
	s_setprio 0
	s_setprio 1
	v_mfma_f32_16x16x32_bf16 v[124:127], v[144:147], v[160:163], 0
	v_mfma_f32_16x16x32_bf16 v[120:123], v[152:155], v[160:163], 0
	v_mfma_f32_16x16x32_bf16 v[108:111], v[144:147], v[196:199], 0
	v_mfma_f32_16x16x32_bf16 v[104:107], v[152:155], v[196:199], 0
	v_mfma_f32_16x16x32_bf16 v[92:95], v[144:147], v[204:207], 0
	v_mfma_f32_16x16x32_bf16 v[88:91], v[152:155], v[204:207], 0
	v_mfma_f32_16x16x32_bf16 v[68:71], v[144:147], v[212:215], 0
	v_mfma_f32_16x16x32_bf16 v[64:67], v[152:155], v[212:215], 0
	v_mfma_f32_16x16x32_bf16 v[124:127], v[148:151], v[164:167], v[124:127]
	v_mfma_f32_16x16x32_bf16 v[120:123], v[156:159], v[164:167], v[120:123]
	v_mfma_f32_16x16x32_bf16 v[108:111], v[148:151], v[200:203], v[108:111]
	v_mfma_f32_16x16x32_bf16 v[104:107], v[156:159], v[200:203], v[104:107]
	v_mfma_f32_16x16x32_bf16 v[92:95], v[148:151], v[208:211], v[92:95]
	v_mfma_f32_16x16x32_bf16 v[88:91], v[156:159], v[208:211], v[88:91]
	v_mfma_f32_16x16x32_bf16 v[68:71], v[148:151], v[216:219], v[68:71]
	v_mfma_f32_16x16x32_bf16 v[64:67], v[156:159], v[216:219], v[64:67]
	s_setprio 0
	s_barrier
	s_add_i32 m0, s15, 0x10000
	ds_read_b128 v[160:163], v232 offset:16384
	ds_read_b128 v[164:167], v246 offset:16384
	ds_read_b128 v[196:199], v232 offset:18432
	ds_read_b128 v[200:203], v246 offset:18432
	ds_read_b128 v[204:207], v232 offset:20480
	ds_read_b128 v[208:211], v246 offset:20480
	ds_read_b128 v[212:215], v232 offset:22528
	ds_read_b128 v[216:219], v246 offset:22528
	global_load_lds_dwordx4 v168, s[52:53]
	s_add_i32 m0, s15, 0x12000
	s_add_u32 s94, s52, 0x80
	s_addc_u32 s95, s53, 0
	global_load_lds_dwordx4 v186, s[52:53]
	s_add_u32 s52, s52, s12
	s_addc_u32 s53, s53, 0
	s_add_i32 m0, s15, 0x14000
	s_add_u32 s98, s24, 0x80
	s_addc_u32 s99, s25, 0
	global_load_lds_dwordx4 v168, s[52:53]
	s_add_i32 m0, s15, 0x16000
	s_nop 0
	global_load_lds_dwordx4 v186, s[52:53]
	s_mov_b32 m0, s20
	s_nop 0
	global_load_lds_dwordx4 v190, s[24:25]
	s_mov_b32 m0, s21
	s_nop 0
	global_load_lds_dwordx4 v188, s[24:25]
	s_cmp_eq_u32 s48, 1
	s_cbranch_scc1 .Lstrict_g2_1
	s_waitcnt vmcnt(12)
	s_branch .Ljoinw_g2_1

; #define PG8_STAGE(bufoff, gbase, voff) do { _Pragma("unroll") for (int _i = 0; _i < 2; ++_i) \
;         __builtin_amdgcn_global_load_lds((const unsigned*)((const char*)(gbase) + (voff)[_i]), (PG8_LAS unsigned*)(lds + (bufoff) + ldsw + _i * 8192), 16, 0, 0); } while (0)
; #define PG8_LDA(dst, b, h) do { _Pragma("unroll") for (int m = 0; m < 4; ++m) _Pragma("unroll") for (int k = 0; k < 2; ++k) dst[m][k] = *(const PG8_LAS bf16x8*)(lds + PG8_SA(b, h) + aoff + m * 2048 + k * 1024); } while (0)
; #define PG8_LDB(dst, b, h) do { _Pragma("unroll") for (int n = 0; n < 2; ++n) _Pragma("unroll") for (int k = 0; k < 2; ++k) dst[n][k] = *(const PG8_LAS bf16x8*)(lds + PG8_SB(b, h) + boff + n * 2048 + k * 1024); } while (0)
; #define PG8_MMA(ai, bj, At, Bt) do { __builtin_amdgcn_s_setprio(1); _Pragma("unroll") for (int m = 0; m < 4; ++m) _Pragma("unroll") for (int n = 0; n < 2; ++n) _Pragma("unroll") for (int k = 0; k < 2; ++k) \
;         acc[ai][bj][m][n] = __builtin_amdgcn_mfma_f32_16x16x32_bf16(Bt[n][k], At[m][k], acc[ai][bj][m][n], 0, 0, 0); __builtin_amdgcn_s_setprio(0); } while (0)
; #define PG8_WAIT_V(n) asm volatile("s_waitcnt vmcnt(" #n ")" ::: "memory")
; #define PG8_WAIT_L(n) asm volatile("s_waitcnt lgkmcnt(" #n ")" ::: "memory")
; #define PG8_BAR __builtin_amdgcn_s_barrier()
; #define PG8_SCHED __builtin_amdgcn_sched_barrier(0)
; template <class Epi, class Sched, bool ALIGN_EPI = false, bool SP2 = false>
; __device__ __forceinline__ void gemm_phase(PG8_LAS unsigned char* lds, const int tid, const Gemm g, const Sched& S, const Epi& E) {
;     ...
;             PG8_LDB(B0, 0, 0); PG8_LDB(B1, 0, 1); PG8_SCHED; PG8_LDA(At, 0, 0); PG8_STAGE(PG8_SA(1, 1), a1 + hstep, voffA);
;             PG8_WAIT_V(8); PG8_WAIT_L(0); PG8_BAR; PG8_MMA(0, 0, At, B0); PG8_MMA(0, 1, At, B1); PG8_BAR; PG8_SCHED;
;             PG8_LDA(At, 0, 1); PG8_STAGE(PG8_SB(0, 0), b2, voffB); PG8_STAGE(PG8_SB(0, 1), b2 + hstep, voffB); PG8_STAGE(PG8_SA(0, 0), a2, voffA);
;             PG8_WAIT_V(8); PG8_WAIT_L(0); PG8_BAR; PG8_MMA(1, 0, At, B0); PG8_MMA(1, 1, At, B1); PG8_BAR; PG8_SCHED;
.Ljoinw_g2_1:
	s_waitcnt lgkmcnt(0)
	s_barrier
	s_setprio 1
	s_waitcnt lgkmcnt(0)
	v_mfma_f32_16x16x32_bf16 v[60:63], v[72:75], v[160:163], 0
	v_mfma_f32_16x16x32_bf16 v[56:59], v[136:139], v[160:163], 0
	v_mfma_f32_16x16x32_bf16 v[44:47], v[72:75], v[196:199], 0
	v_mfma_f32_16x16x32_bf16 v[40:43], v[136:139], v[196:199], 0
	v_mfma_f32_16x16x32_bf16 v[28:31], v[72:75], v[204:207], 0
	v_mfma_f32_16x16x32_bf16 v[24:27], v[136:139], v[204:207], 0
	v_mfma_f32_16x16x32_bf16 v[12:15], v[72:75], v[212:215], 0
	v_mfma_f32_16x16x32_bf16 v[8:11], v[136:139], v[212:215], 0
	v_mfma_f32_16x16x32_bf16 v[60:63], v[76:79], v[164:167], v[60:63]
	v_mfma_f32_16x16x32_bf16 v[56:59], v[140:143], v[164:167], v[56:59]
	v_mfma_f32_16x16x32_bf16 v[44:47], v[76:79], v[200:203], v[44:47]
	v_mfma_f32_16x16x32_bf16 v[40:43], v[140:143], v[200:203], v[40:43]
	v_mfma_f32_16x16x32_bf16 v[28:31], v[76:79], v[208:211], v[28:31]
	v_mfma_f32_16x16x32_bf16 v[24:27], v[140:143], v[208:211], v[24:27]
	v_mfma_f32_16x16x32_bf16 v[12:15], v[76:79], v[216:219], v[12:15]
	v_mfma_f32_16x16x32_bf16 v[8:11], v[140:143], v[216:219], v[8:11]
	s_setprio 0
	s_setprio 1
	v_mfma_f32_16x16x32_bf16 v[52:55], v[144:147], v[160:163], 0
	v_mfma_f32_16x16x32_bf16 v[48:51], v[152:155], v[160:163], 0
	v_mfma_f32_16x16x32_bf16 v[36:39], v[144:147], v[196:199], 0
	v_mfma_f32_16x16x32_bf16 v[32:35], v[152:155], v[196:199], 0
	v_mfma_f32_16x16x32_bf16 v[20:23], v[144:147], v[204:207], 0
	v_mfma_f32_16x16x32_bf16 v[16:19], v[152:155], v[204:207], 0
	v_mfma_f32_16x16x32_bf16 v[4:7], v[144:147], v[212:215], 0
	v_mfma_f32_16x16x32_bf16 v[0:3], v[152:155], v[212:215], 0
	v_mfma_f32_16x16x32_bf16 v[52:55], v[148:151], v[164:167], v[52:55]
	v_mfma_f32_16x16x32_bf16 v[48:51], v[156:159], v[164:167], v[48:51]
	v_mfma_f32_16x16x32_bf16 v[36:39], v[148:151], v[200:203], v[36:39]
	v_mfma_f32_16x16x32_bf16 v[32:35], v[156:159], v[200:203], v[32:35]
	v_mfma_f32_16x16x32_bf16 v[20:23], v[148:151], v[208:211], v[20:23]
	v_mfma_f32_16x16x32_bf16 v[16:19], v[156:159], v[208:211], v[16:19]
	v_mfma_f32_16x16x32_bf16 v[4:7], v[148:151], v[216:219], v[4:7]
	v_mfma_f32_16x16x32_bf16 v[0:3], v[156:159], v[216:219], v[0:3]
	s_setprio 0
	s_barrier
	ds_read_b128 v[72:75], v247 offset:32768
	ds_read_b128 v[76:79], v248 offset:32768
	ds_read_b128 v[136:139], v247 offset:34816
	ds_read_b128 v[140:143], v248 offset:34816
	ds_read_b128 v[144:147], v247 offset:49152
	ds_read_b128 v[148:151], v248 offset:49152
	ds_read_b128 v[152:155], v247 offset:51200
	ds_read_b128 v[156:159], v248 offset:51200
	s_add_u32 s24, s24, s12
	s_addc_u32 s25, s25, 0
	s_mov_b32 m0, s22
	ds_read_b128 v[160:163], v232 offset:32768
	ds_read_b128 v[164:167], v246 offset:32768
	ds_read_b128 v[196:199], v232 offset:34816
	ds_read_b128 v[200:203], v246 offset:34816
	ds_read_b128 v[204:207], v232 offset:36864
	ds_read_b128 v[208:211], v246 offset:36864
	ds_read_b128 v[212:215], v232 offset:38912
	ds_read_b128 v[216:219], v246 offset:38912
	global_load_lds_dwordx4 v190, s[24:25]
	s_mov_b32 m0, s23
	s_nop 0
	global_load_lds_dwordx4 v188, s[24:25]
	s_waitcnt vmcnt(8)
	s_waitcnt lgkmcnt(0)
	s_barrier
	s_setprio 1
	s_waitcnt lgkmcnt(0)
	v_mfma_f32_16x16x32_bf16 v[132:135], v[72:75], v[160:163], v[132:135]
	v_mfma_f32_16x16x32_bf16 v[128:131], v[136:139], v[160:163], v[128:131]
	v_mfma_f32_16x16x32_bf16 v[116:119], v[72:75], v[196:199], v[116:119]
	v_mfma_f32_16x16x32_bf16 v[112:115], v[136:139], v[196:199], v[112:115]
	v_mfma_f32_16x16x32_bf16 v[100:103], v[72:75], v[204:207], v[100:103]
	v_mfma_f32_16x16x32_bf16 v[96:99], v[136:139], v[204:207], v[96:99]
	v_mfma_f32_16x16x32_bf16 v[84:87], v[72:75], v[212:215], v[84:87]
	v_mfma_f32_16x16x32_bf16 v[80:83], v[136:139], v[212:215], v[80:83]
	v_mfma_f32_16x16x32_bf16 v[132:135], v[76:79], v[164:167], v[132:135]
	v_mfma_f32_16x16x32_bf16 v[128:131], v[140:143], v[164:167], v[128:131]
	v_mfma_f32_16x16x32_bf16 v[116:119], v[76:79], v[200:203], v[116:119]
	v_mfma_f32_16x16x32_bf16 v[112:115], v[140:143], v[200:203], v[112:115]
	v_mfma_f32_16x16x32_bf16 v[100:103], v[76:79], v[208:211], v[100:103]
	v_mfma_f32_16x16x32_bf16 v[96:99], v[140:143], v[208:211], v[96:99]
	v_mfma_f32_16x16x32_bf16 v[84:87], v[76:79], v[216:219], v[84:87]
	v_mfma_f32_16x16x32_bf16 v[80:83], v[140:143], v[216:219], v[80:83]
	s_setprio 0
	s_setprio 1
	v_mfma_f32_16x16x32_bf16 v[124:127], v[144:147], v[160:163], v[124:127]
	v_mfma_f32_16x16x32_bf16 v[120:123], v[152:155], v[160:163], v[120:123]
	v_mfma_f32_16x16x32_bf16 v[108:111], v[144:147], v[196:199], v[108:111]
	v_mfma_f32_16x16x32_bf16 v[104:107], v[152:155], v[196:199], v[104:107]
	v_mfma_f32_16x16x32_bf16 v[92:95], v[144:147], v[204:207], v[92:95]
	v_mfma_f32_16x16x32_bf16 v[88:91], v[152:155], v[204:207], v[88:91]
	v_mfma_f32_16x16x32_bf16 v[68:71], v[144:147], v[212:215], v[68:71]
	v_mfma_f32_16x16x32_bf16 v[64:67], v[152:155], v[212:215], v[64:67]
	v_mfma_f32_16x16x32_bf16 v[124:127], v[148:151], v[164:167], v[124:127]
	v_mfma_f32_16x16x32_bf16 v[120:123], v[156:159], v[164:167], v[120:123]
	v_mfma_f32_16x16x32_bf16 v[108:111], v[148:151], v[200:203], v[108:111]
	v_mfma_f32_16x16x32_bf16 v[104:107], v[156:159], v[200:203], v[104:107]
	v_mfma_f32_16x16x32_bf16 v[92:95], v[148:151], v[208:211], v[92:95]
	v_mfma_f32_16x16x32_bf16 v[88:91], v[156:159], v[208:211], v[88:91]
	v_mfma_f32_16x16x32_bf16 v[68:71], v[148:151], v[216:219], v[68:71]
	v_mfma_f32_16x16x32_bf16 v[64:67], v[156:159], v[216:219], v[64:67]
	s_setprio 0
	s_barrier
; #define PG8_STAGE(bufoff, gbase, voff) do { _Pragma("unroll") for (int _i = 0; _i < 2; ++_i) \
;         __builtin_amdgcn_global_load_lds((const unsigned*)((const char*)(gbase) + (voff)[_i]), (PG8_LAS unsigned*)(lds + (bufoff) + ldsw + _i * 8192), 16, 0, 0); } while (0)
; #define PG8_LDA(dst, b, h) do { _Pragma("unroll") for (int m = 0; m < 4; ++m) _Pragma("unroll") for (int k = 0; k < 2; ++k) dst[m][k] = *(const PG8_LAS bf16x8*)(lds + PG8_SA(b, h) + aoff + m * 2048 + k * 1024); } while (0)
; #define PG8_LDB(dst, b, h) do { _Pragma("unroll") for (int n = 0; n < 2; ++n) _Pragma("unroll") for (int k = 0; k < 2; ++k) dst[n][k] = *(const PG8_LAS bf16x8*)(lds + PG8_SB(b, h) + boff + n * 2048 + k * 1024); } while (0)
; #define PG8_MMA(ai, bj, At, Bt) do { __builtin_amdgcn_s_setprio(1); _Pragma("unroll") for (int m = 0; m < 4; ++m) _Pragma("unroll") for (int n = 0; n < 2; ++n) _Pragma("unroll") for (int k = 0; k < 2; ++k) \
;         acc[ai][bj][m][n] = __builtin_amdgcn_mfma_f32_16x16x32_bf16(Bt[n][k], At[m][k], acc[ai][bj][m][n], 0, 0, 0); __builtin_amdgcn_s_setprio(0); } while (0)
; #define PG8_WAIT_V(n) asm volatile("s_waitcnt vmcnt(" #n ")" ::: "memory")
; #define PG8_WAIT_L(n) asm volatile("s_waitcnt lgkmcnt(" #n ")" ::: "memory")
; #define PG8_BAR __builtin_amdgcn_s_barrier()
; template <class Epi, class Sched, bool ALIGN_EPI = false, bool SP2 = false>
; __device__ __forceinline__ void gemm_phase(PG8_LAS unsigned char* lds, const int tid, const Gemm g, const Sched& S, const Epi& E) {
;     ...
;         for (int t = 0; t < nt; t += 2) {
;             const bool last = (t == nt - 2);
;             const char* a1 = cA + (size_t)(t + 1) * kstep;
;             const char* a2 = last ? nA : cA + (size_t)(t + 2) * kstep; const char* b2 = last ? nB : cB + (size_t)(t + 2) * kstep;
;             const char* a3 = a2 + kstep; const char* b3 = b2 + kstep;
;     ...
;             PG8_LDB(B0, 1, 0); PG8_LDB(B1, 1, 1); PG8_SCHED; PG8_LDA(At, 1, 0); PG8_STAGE(PG8_SA(0, 1), a2 + hstep, voffA);
;             PG8_WAIT_V(8); PG8_WAIT_L(0); PG8_BAR; PG8_MMA(0, 0, At, B0); PG8_MMA(0, 1, At, B1); PG8_BAR; PG8_SCHED;
;             PG8_LDA(At, 1, 1); PG8_STAGE(PG8_SB(1, 0), b3, voffB); PG8_STAGE(PG8_SB(1, 1), b3 + hstep, voffB); PG8_STAGE(PG8_SA(1, 0), a3, voffA);
;             PG8_WAIT_V(8); PG8_WAIT_L(0); PG8_BAR; PG8_MMA(1, 0, At, B0); PG8_MMA(1, 1, At, B1); PG8_BAR; PG8_SCHED;
	s_add_u32 s96, s52, 0x80
	s_addc_u32 s97, s53, 0
	s_add_i32 m0, s15, 0x18000
	ds_read_b128 v[160:163], v232 offset:49152
	ds_read_b128 v[164:167], v246 offset:49152
	ds_read_b128 v[196:199], v232 offset:51200
	ds_read_b128 v[200:203], v246 offset:51200
	ds_read_b128 v[204:207], v232 offset:53248
	ds_read_b128 v[208:211], v246 offset:53248
	ds_read_b128 v[212:215], v232 offset:55296
	ds_read_b128 v[216:219], v246 offset:55296
	global_load_lds_dwordx4 v168, s[94:95]
	s_add_i32 m0, s15, 0x1a000
	s_nop 0
	global_load_lds_dwordx4 v186, s[94:95]
	s_add_i32 m0, s15, 0x1c000
	s_nop 0
	global_load_lds_dwordx4 v168, s[96:97]
	s_add_i32 m0, s15, 0x1e000
	s_nop 0
	global_load_lds_dwordx4 v186, s[96:97]
	s_mov_b32 m0, s45
	s_nop 0
	global_load_lds_dwordx4 v190, s[98:99]
	s_mov_b32 m0, s46
	s_nop 0
	global_load_lds_dwordx4 v188, s[98:99]
	s_waitcnt vmcnt(8)
	s_waitcnt lgkmcnt(0)
	s_barrier
	s_setprio 1
	s_waitcnt lgkmcnt(0)
	v_mfma_f32_16x16x32_bf16 v[60:63], v[72:75], v[160:163], v[60:63]
	v_mfma_f32_16x16x32_bf16 v[56:59], v[136:139], v[160:163], v[56:59]
	v_mfma_f32_16x16x32_bf16 v[44:47], v[72:75], v[196:199], v[44:47]
	v_mfma_f32_16x16x32_bf16 v[40:43], v[136:139], v[196:199], v[40:43]
	v_mfma_f32_16x16x32_bf16 v[28:31], v[72:75], v[204:207], v[28:31]
	v_mfma_f32_16x16x32_bf16 v[24:27], v[136:139], v[204:207], v[24:27]
	v_mfma_f32_16x16x32_bf16 v[12:15], v[72:75], v[212:215], v[12:15]
	v_mfma_f32_16x16x32_bf16 v[8:11], v[136:139], v[212:215], v[8:11]
	v_mfma_f32_16x16x32_bf16 v[60:63], v[76:79], v[164:167], v[60:63]
	v_mfma_f32_16x16x32_bf16 v[56:59], v[140:143], v[164:167], v[56:59]
	v_mfma_f32_16x16x32_bf16 v[44:47], v[76:79], v[200:203], v[44:47]
	v_mfma_f32_16x16x32_bf16 v[40:43], v[140:143], v[200:203], v[40:43]
	v_mfma_f32_16x16x32_bf16 v[28:31], v[76:79], v[208:211], v[28:31]
	v_mfma_f32_16x16x32_bf16 v[24:27], v[140:143], v[208:211], v[24:27]
	v_mfma_f32_16x16x32_bf16 v[12:15], v[76:79], v[216:219], v[12:15]
	v_mfma_f32_16x16x32_bf16 v[8:11], v[140:143], v[216:219], v[8:11]
	s_setprio 0
	s_setprio 1
	v_mfma_f32_16x16x32_bf16 v[52:55], v[144:147], v[160:163], v[52:55]
	v_mfma_f32_16x16x32_bf16 v[48:51], v[152:155], v[160:163], v[48:51]
	v_mfma_f32_16x16x32_bf16 v[36:39], v[144:147], v[196:199], v[36:39]
	v_mfma_f32_16x16x32_bf16 v[32:35], v[152:155], v[196:199], v[32:35]
	v_mfma_f32_16x16x32_bf16 v[20:23], v[144:147], v[204:207], v[20:23]
	v_mfma_f32_16x16x32_bf16 v[16:19], v[152:155], v[204:207], v[16:19]
	v_mfma_f32_16x16x32_bf16 v[4:7], v[144:147], v[212:215], v[4:7]
	v_mfma_f32_16x16x32_bf16 v[0:3], v[152:155], v[212:215], v[0:3]
	v_mfma_f32_16x16x32_bf16 v[52:55], v[148:151], v[164:167], v[52:55]
	v_mfma_f32_16x16x32_bf16 v[48:51], v[156:159], v[164:167], v[48:51]
	v_mfma_f32_16x16x32_bf16 v[36:39], v[148:151], v[200:203], v[36:39]
	v_mfma_f32_16x16x32_bf16 v[32:35], v[156:159], v[200:203], v[32:35]
	v_mfma_f32_16x16x32_bf16 v[20:23], v[148:151], v[208:211], v[20:23]
	v_mfma_f32_16x16x32_bf16 v[16:19], v[156:159], v[208:211], v[16:19]
	v_mfma_f32_16x16x32_bf16 v[4:7], v[148:151], v[216:219], v[4:7]
	v_mfma_f32_16x16x32_bf16 v[0:3], v[156:159], v[216:219], v[0:3]
	s_setprio 0
	s_barrier
	s_add_u32 s38, s38, 0x100
	s_addc_u32 s39, s39, 0
	s_add_u32 s26, s26, 0x100
	s_addc_u32 s27, s27, 0
	s_cmp_ge_u32 s51, s44
	s_mov_b32 s14, s51
	s_cbranch_scc0 .LBB0_311
	s_branch .Lpeel_exit_g2
